# on top of keep6+lds2: six second-half MIXB (prev) loads issued at the top of the F1 epilogue (their registers are idle in the first half now)
# baseline (speedup 1.0000x reference)
.LBB0_880:
	v_lshlrev_b32_e32 v252, 4, v216
	v_add_u32_e32 v252, 0x21000, v252
	s_mov_b32 s98, s7
	s_cmp_eq_u32 s98, 0
	s_cbranch_scc1 .Lf1e_201
	s_lshl_b32 s99, s6, 8
	v_add_u32_e32 v253, s99, v217
	v_add_u32_e32 v253, 0x80, v253
	v_lshlrev_b32_e32 v253, 12, v253
	v_lshl_or_b32 v254, s49, 8, v222
	v_lshl_add_u32 v253, v254, 1, v253
	global_load_dwordx4 v[132:135], v253, s[10:11]
	global_load_dwordx4 v[120:123], v253, s[10:11] offset:256
	v_add_u32_e32 v254, 0x10000, v253
	global_load_dwordx4 v[108:111], v254, s[10:11]
	global_load_dwordx4 v[100:103], v254, s[10:11] offset:256
	v_add_u32_e32 v254, 0x20000, v253
	global_load_dwordx4 v[88:91], v254, s[10:11]
	global_load_dwordx4 v[80:83], v254, s[10:11] offset:256
.Lf1e_201:
	s_lshl_b32 s22, s7, 11
	s_ashr_i32 s23, s22, 31
	s_cmp_lg_u32 s7, 0
	s_cselect_b64 s[24:25], -1, 0
	s_lshl_b32 s17, s6, 8
	s_lshl_b64 s[22:23], s[22:23], 1
	v_add_u32_e32 v210, s17, v217
	s_add_u32 s22, s39, s22
	v_ashrrev_i32_e32 v211, 31, v210
	s_addc_u32 s23, s40, s23
	v_lshl_or_b32 v208, s49, 8, v222
	v_lshlrev_b64 v[64:65], 14, v[210:211]
	v_lshl_add_u64 v[64:65], s[22:23], 0, v[64:65]
	v_ashrrev_i32_e32 v209, 31, v208
	v_lshl_add_u64 v[64:65], v[208:209], 1, v[64:65]
	global_load_dwordx4 v[188:191], v[64:65], off
	v_lshlrev_b64 v[66:67], 12, v[210:211]
	v_lshl_add_u64 v[66:67], s[10:11], 0, v[66:67]
	s_cmp_eq_u32 s7, 0
	v_lshl_add_u64 v[212:213], v[208:209], 1, v[66:67]
	s_cbranch_scc1 .LBB0_882

.Lf1k_103:
	v_add_u32_e32 v72, 0x80, v210
	v_ashrrev_i32_e32 v73, 31, v72
	v_lshlrev_b64 v[74:75], 14, v[72:73]
	v_lshl_add_u64 v[74:75], s[22:23], 0, v[74:75]
	v_lshl_add_u64 v[74:75], v[208:209], 1, v[74:75]
	global_load_dwordx4 v[116:119], v[74:75], off
	v_lshlrev_b64 v[76:77], 12, v[72:73]
	v_lshl_add_u64 v[76:77], s[10:11], 0, v[76:77]
	s_and_b64 vcc, exec, s[6:7]
	v_lshl_add_u64 v[124:125], v[208:209], 1, v[76:77]
	s_cbranch_vccnz .LBB0_914
.LBB0_914:
	global_load_dwordx4 v[112:115], v[74:75], off offset:256
	s_and_b64 vcc, exec, s[6:7]
	s_cbranch_vccnz .LBB0_916
.LBB0_916:
	v_or_b32_e32 v74, 16, v72
	v_ashrrev_i32_e32 v75, 31, v74
	v_lshlrev_b64 v[76:77], 14, v[74:75]
	v_lshl_add_u64 v[76:77], s[22:23], 0, v[76:77]
	v_lshl_add_u64 v[76:77], v[208:209], 1, v[76:77]
	global_load_dwordx4 v[104:107], v[76:77], off
	v_lshlrev_b64 v[74:75], 12, v[74:75]
	v_lshl_add_u64 v[74:75], s[10:11], 0, v[74:75]
	s_and_b64 vcc, exec, s[6:7]
	v_lshl_add_u64 v[74:75], v[208:209], 1, v[74:75]
	s_cbranch_vccnz .LBB0_918
.LBB0_918:
	global_load_dwordx4 v[96:99], v[76:77], off offset:256
	s_and_b64 vcc, exec, s[6:7]
	s_cbranch_vccnz .LBB0_920
.LBB0_920:
	v_or_b32_e32 v74, 32, v72
	v_ashrrev_i32_e32 v75, 31, v74
	v_lshlrev_b64 v[76:77], 14, v[74:75]
	v_lshl_add_u64 v[76:77], s[22:23], 0, v[76:77]
	v_lshl_add_u64 v[76:77], v[208:209], 1, v[76:77]
	global_load_dwordx4 v[92:95], v[76:77], off
	v_lshlrev_b64 v[74:75], 12, v[74:75]
	v_lshl_add_u64 v[74:75], s[10:11], 0, v[74:75]
	s_and_b64 vcc, exec, s[6:7]
	v_lshl_add_u64 v[74:75], v[208:209], 1, v[74:75]
	s_cbranch_vccnz .LBB0_922
.LBB0_922:
	global_load_dwordx4 v[84:87], v[76:77], off offset:256
	s_and_b64 vcc, exec, s[6:7]
	s_cbranch_vccnz .LBB0_924
.LBB0_924:
	v_or_b32_e32 v74, 48, v72
	v_ashrrev_i32_e32 v75, 31, v74
	v_lshlrev_b64 v[72:73], 14, v[74:75]
	v_lshl_add_u64 v[72:73], s[22:23], 0, v[72:73]
	v_lshl_add_u64 v[72:73], v[208:209], 1, v[72:73]
	global_load_dwordx4 v[76:79], v[72:73], off
	v_lshlrev_b64 v[74:75], 12, v[74:75]
	v_lshl_add_u64 v[74:75], s[10:11], 0, v[74:75]
	s_and_b64 vcc, exec, s[6:7]
	v_lshl_add_u64 v[126:127], v[208:209], 1, v[74:75]
	s_cbranch_vccnz .LBB0_926
	global_load_dwordx4 v[68:71], v[126:127], off

.Lf1k_101:
	v_add_u32_e32 v72, 0x80, v210
	v_ashrrev_i32_e32 v73, 31, v72
	v_lshlrev_b64 v[74:75], 14, v[72:73]
	v_lshl_add_u64 v[74:75], s[22:23], 0, v[74:75]
	v_lshl_add_u64 v[74:75], v[208:209], 1, v[74:75]
	global_load_dwordx4 v[116:119], v[74:75], off
	v_lshlrev_b64 v[76:77], 12, v[72:73]
	v_lshl_add_u64 v[76:77], s[10:11], 0, v[76:77]
	s_and_b64 vcc, exec, s[6:7]
	v_lshl_add_u64 v[124:125], v[208:209], 1, v[76:77]
	s_cbranch_vccnz .LBB0_1968
.LBB0_1968:
	global_load_dwordx4 v[112:115], v[74:75], off offset:256
	s_and_b64 vcc, exec, s[6:7]
	s_cbranch_vccnz .LBB0_1970
.LBB0_1970:
	v_or_b32_e32 v74, 16, v72
	v_ashrrev_i32_e32 v75, 31, v74
	v_lshlrev_b64 v[76:77], 14, v[74:75]
	v_lshl_add_u64 v[76:77], s[22:23], 0, v[76:77]
	v_lshl_add_u64 v[76:77], v[208:209], 1, v[76:77]
	global_load_dwordx4 v[104:107], v[76:77], off
	v_lshlrev_b64 v[74:75], 12, v[74:75]
	v_lshl_add_u64 v[74:75], s[10:11], 0, v[74:75]
	s_and_b64 vcc, exec, s[6:7]
	v_lshl_add_u64 v[74:75], v[208:209], 1, v[74:75]
	s_cbranch_vccnz .LBB0_1972
.LBB0_1972:
	global_load_dwordx4 v[96:99], v[76:77], off offset:256
	s_and_b64 vcc, exec, s[6:7]
	s_cbranch_vccnz .LBB0_1974
.LBB0_1974:
	v_or_b32_e32 v74, 32, v72
	v_ashrrev_i32_e32 v75, 31, v74
	v_lshlrev_b64 v[76:77], 14, v[74:75]
	v_lshl_add_u64 v[76:77], s[22:23], 0, v[76:77]
	v_lshl_add_u64 v[76:77], v[208:209], 1, v[76:77]
	global_load_dwordx4 v[92:95], v[76:77], off
	v_lshlrev_b64 v[74:75], 12, v[74:75]
	v_lshl_add_u64 v[74:75], s[10:11], 0, v[74:75]
	s_and_b64 vcc, exec, s[6:7]
	v_lshl_add_u64 v[74:75], v[208:209], 1, v[74:75]
	s_cbranch_vccnz .LBB0_1976
.LBB0_1976:
	global_load_dwordx4 v[84:87], v[76:77], off offset:256
	s_and_b64 vcc, exec, s[6:7]
	s_cbranch_vccnz .LBB0_1978
.LBB0_1978:
	v_or_b32_e32 v74, 48, v72
	v_ashrrev_i32_e32 v75, 31, v74
	v_lshlrev_b64 v[72:73], 14, v[74:75]
	v_lshl_add_u64 v[72:73], s[22:23], 0, v[72:73]
	v_lshl_add_u64 v[72:73], v[208:209], 1, v[72:73]
	global_load_dwordx4 v[76:79], v[72:73], off
	v_lshlrev_b64 v[74:75], 12, v[74:75]
	v_lshl_add_u64 v[74:75], s[10:11], 0, v[74:75]
	s_and_b64 vcc, exec, s[6:7]
	v_lshl_add_u64 v[126:127], v[208:209], 1, v[74:75]
	s_cbranch_vccnz .LBB0_1980
	global_load_dwordx4 v[68:71], v[126:127], off
